# carry scan fused into the S5 output GEMM phase (each block scans the 512 recurrences its own unit consumes); one grid barrier fewer
# baseline (speedup 1.0000x reference)
.LBB0_544:
	s_or_b64 exec, exec, s[0:1]
	s_waitcnt lgkmcnt(0)
	s_and_b32 s98, s6, 7
	s_lshl_b32 s98, s98, 5
	s_lshr_b32 s99, s6, 3
	s_add_i32 s98, s98, s99
	s_and_b32 s98, s98, 0xfe
	v_mov_b32_e32 v0, 0x6050400
	v_perm_b32 v0, s98, v193, v0
	v_and_b32_e32 v1, 0x300, v193
	v_mad_u64_u32 v[0:1], s[0:1], 1, v1, v[0:1]
	s_mov_b32 s2, 0x10000
	v_cmp_gt_i32_e32 vcc, s2, v0
	v_and_b32_e32 v192, 63, v193
	s_barrier
	s_and_saveexec_b64 s[0:1], vcc
	s_cbranch_execz .LBB0_551
	v_mov_b32_e32 v3, 0
	v_lshlrev_b32_e32 v2, 3, v192
	v_lshl_add_u64 v[4:5], s[90:91], 0, v[2:3]
	s_mov_b64 s[4:5], 0x3fe0000
	s_lshl_b32 s3, s92, 9
	v_lshl_add_u64 v[4:5], v[4:5], 0, s[4:5]
	s_mov_b64 s[4:5], 0
	s_movk_i32 s7, 0x4000
	s_movk_i32 s12, 0x3c0
	v_lshlrev_b32_e32 v6, 2, v192
	v_mov_b32_e32 v7, v3
	s_movk_i32 s13, 0x600
	v_mov_b64_e32 v[8:9], s[90:91]
	v_lshlrev_b32_e32 v10, 1, v192
	v_mov_b32_e32 v11, v3
	s_mov_b64 s[8:9], 0x88f0400
	s_movk_i32 s14, 0x1000
	s_movk_i32 s15, 0x2000
	s_movk_i32 s16, 0x3000
	s_movk_i32 s17, 0x5000
	s_movk_i32 s33, 0x6000
	s_movk_i32 s34, 0x7000
	s_mov_b32 s35, 0x8000
	s_mov_b32 s38, 0x9000
	s_mov_b32 s39, 0xa000
	s_mov_b32 s40, 0xb000
	s_mov_b32 s41, 0xc000
	s_mov_b32 s42, 0xd000
	s_mov_b32 s43, 0xe000
	s_mov_b32 s44, 0xf000
	s_mov_b32 s45, 0x17000
	s_mov_b32 s48, 0x16000
	s_mov_b32 s49, 0x15000
	s_mov_b32 s50, 0x14000
	s_mov_b32 s51, 0x13000
	s_mov_b32 s54, 0x12000
	s_mov_b32 s55, 0x11000
	s_mov_b32 s56, 0xffff
	s_branch .LBB0_547

.LBB0_589:
	s_cmp_eq_u32 s101, 1
	s_cbranch_scc1 .Llt_p3_return
	s_waitcnt vmcnt(0)
	s_barrier
	s_and_saveexec_b64 s[0:1], s[80:81]
	s_cbranch_execz .LBB0_641
.LBB0_641:
	s_or_b64 exec, exec, s[0:1]
	s_mov_b32 s101, s6
	s_and_b32 s98, s6, 7
	s_lshl_b32 s98, s98, 5
	s_lshr_b32 s6, s6, 3
	s_add_i32 s6, s6, s98
	v_mov_b32_e32 v9, v193
	s_cmpk_lt_i32 s6, 0x100
	s_waitcnt lgkmcnt(0)
	s_barrier
	s_cselect_b64 s[0:1], -1, 0
	s_cmpk_gt_i32 s6, 0xff
	v_readfirstlane_b32 s3, v9
	s_cbranch_scc1 .LBB0_657
	v_lshlrev_b32_e32 v0, 4, v9
	v_add_u32_e32 v1, 0x2000, v0
	v_ashrrev_i32_e32 v2, 31, v1
	v_lshrrev_b32_e32 v2, 22, v2
	v_add_u32_e32 v2, v1, v2
	v_ashrrev_i32_e32 v8, 10, v2
	v_mul_i32_i24_e32 v2, 0x400, v8
	v_sub_u32_e32 v1, v1, v2
	v_lshrrev_b32_e32 v2, 4, v1
	v_bitop3_b32 v1, v2, v1, 32 bitop3:0x6c
	v_ashrrev_i32_e32 v2, 31, v1
	v_lshrrev_b32_e32 v2, 26, v2
	v_add_u32_e32 v2, v1, v2
	v_lshlrev_b32_e32 v3, 3, v8
	v_ashrrev_i32_e32 v10, 6, v2
	v_and_b32_e32 v3, -16, v3
	v_add_u32_e32 v3, v10, v3
	v_and_b32_e32 v4, 3, v10
	s_mov_b32 s2, 0xffffe0
	v_lshrrev_b32_e32 v5, 2, v3
	v_lshlrev_b32_e32 v6, 1, v3
	v_and_b32_e32 v2, 0xc0, v2
	v_and_or_b32 v4, v3, s2, v4
	v_and_b32_e32 v5, 4, v5
	v_and_b32_e32 v6, 24, v6
	v_sub_u32_e32 v1, v1, v2
	v_mov_b32_e32 v2, 1
	v_or3_b32 v4, v4, v5, v6
	v_lshlrev_b32_e32 v5, 5, v8
	v_ashrrev_i16_sdwa v1, v2, sext(v1) dst_sel:DWORD dst_unused:UNUSED_PAD src0_sel:DWORD src1_sel:BYTE_0
	s_movk_i32 s33, 0x300
	v_and_b32_e32 v11, 32, v5
	v_bfe_i32 v12, v1, 0, 16
	v_mul_u32_u24_e32 v4, 0x300, v4
	v_add_u32_e32 v1, v11, v12
	v_mul_lo_u32 v3, v3, s33
	v_add_lshl_u32 v128, v4, v1, 1
	v_add_lshl_u32 v130, v1, v3, 1
	v_bfe_i32 v1, v9, 27, 1
	v_lshrrev_b32_e32 v1, 22, v1
	v_add_u32_e32 v1, v0, v1
	v_and_b32_e32 v1, 0xfffffc00, v1
	v_sub_u32_e32 v0, v0, v1
	v_lshrrev_b32_e32 v1, 4, v0
	v_ashrrev_i32_e32 v3, 31, v9
	v_bitop3_b32 v0, v1, v0, 32 bitop3:0x6c
	v_lshrrev_b32_e32 v3, 26, v3
	v_ashrrev_i32_e32 v1, 31, v0
	v_add_u32_e32 v3, v9, v3
	v_lshrrev_b32_e32 v1, 26, v1
	v_ashrrev_i32_e32 v14, 6, v3
	v_add_u32_e32 v1, v0, v1
	v_lshlrev_b32_e32 v3, 3, v14
	s_add_u32 s66, s90, 0x1f60000
	v_ashrrev_i32_e32 v13, 6, v1
	v_and_b32_e32 v3, -16, v3
	s_addc_u32 s67, s91, 0
	v_add_u32_e32 v3, v13, v3
	v_and_b32_e32 v4, 3, v13
	s_ashr_i32 s9, s6, 31
	v_and_or_b32 v4, v3, s2, v4
	s_lshr_b32 s2, s6, 31
	s_lshr_b32 s9, s9, 29
	s_add_i32 s2, s6, s2
	s_add_i32 s9, s6, s9
	s_and_b32 s8, s2, 0xfffffe
	s_ashr_i32 s54, s9, 3
	s_lshl_b32 s2, s2, 7
	s_sub_i32 s8, s6, s8
	s_and_b32 s2, s2, 0x300
	s_ashr_i32 s55, s54, 31
	s_lshl_b32 s56, s8, 8
	s_lshl_b64 s[8:9], s[54:55], 11
	s_lshl_b32 s11, s2, 1
	s_or_b32 s8, s8, s11
	s_ashr_i32 s10, s3, 6
	s_mulk_i32 s9, 0x300
	s_mul_hi_u32 s11, s8, 0x300
	s_ashr_i32 s7, s3, 8
	s_lshl_b32 s68, s10, 10
	s_add_i32 s11, s11, s9
	s_mulk_i32 s8, 0x300
	s_add_u32 s58, s26, s8
	s_addc_u32 s59, s27, s11
	s_ashr_i32 s57, s56, 31
	s_lshl_b64 s[8:9], s[54:55], 10
	s_lshl_b64 s[30:31], s[56:57], 1
	s_add_u32 s8, s30, s8
	v_lshrrev_b32_e32 v5, 2, v3
	v_lshlrev_b32_e32 v6, 1, v3
	v_and_b32_e32 v1, 0xc0, v1
	s_addc_u32 s9, s31, s9
	v_and_b32_e32 v5, 4, v5
	v_and_b32_e32 v6, 24, v6
	v_sub_u32_e32 v0, v0, v1
	s_mulk_i32 s9, 0x300
	s_mul_hi_u32 s11, s8, 0x300
	v_or3_b32 v4, v4, v5, v6
	v_lshlrev_b32_e32 v5, 5, v14
	v_ashrrev_i16_sdwa v0, v2, sext(v0) dst_sel:DWORD dst_unused:UNUSED_PAD src0_sel:DWORD src1_sel:BYTE_0
	s_add_i32 s11, s11, s9
	s_mulk_i32 s8, 0x300
	v_and_b32_e32 v15, 32, v5
	v_bfe_i32 v16, v0, 0, 16
	s_add_u32 s60, s66, s8
	v_mul_u32_u24_e32 v4, 0x300, v4
	v_add_u32_e32 v0, v15, v16
	s_addc_u32 s61, s67, s11
	s_add_i32 s57, s68, 0
	v_add_lshl_u32 v132, v4, v0, 1
	s_add_i32 m0, s57, 0x10000
	v_mul_lo_u32 v1, v3, s33
	global_load_lds_dwordx4 v132, s[60:61]
	s_add_i32 m0, s57, 0x12000
	s_add_u32 s8, s60, 0x30000
	global_load_lds_dwordx4 v128, s[60:61]
	s_addc_u32 s9, s61, 0
	s_add_i32 m0, s57, 0x14000
	s_add_i32 s69, s57, 0x2000
	global_load_lds_dwordx4 v132, s[8:9]
	s_add_i32 m0, s57, 0x16000
	v_add_lshl_u32 v134, v0, v1, 1
	global_load_lds_dwordx4 v128, s[8:9]
	s_mov_b32 m0, s57
	s_add_u32 s8, s58, 0x30000
	global_load_lds_dwordx4 v134, s[58:59]
	s_mov_b32 m0, s69
	s_addc_u32 s9, s59, 0
	s_add_i32 s70, s57, 0x4000
	global_load_lds_dwordx4 v130, s[58:59]
	s_mov_b32 m0, s70
	s_add_i32 s71, s57, 0x6000
	global_load_lds_dwordx4 v134, s[8:9]
	s_mov_b32 m0, s71
	v_mov_b32_e32 v137, 0
	global_load_lds_dwordx4 v130, s[8:9]
	v_mov_b32_e32 v133, v137
	v_mov_b32_e32 v129, v137
	v_mov_b32_e32 v135, v137
	v_mov_b32_e32 v131, v137
	s_cmp_eq_u32 s7, 1
	s_mov_b32 s72, 0
	v_lshl_add_u64 v[6:7], s[60:61], 0, v[132:133]
	v_lshl_add_u64 v[4:5], s[60:61], 0, v[128:129]
	v_lshl_add_u64 v[0:1], s[58:59], 0, v[134:135]
	s_cselect_b64 s[8:9], -1, 0
	s_cmp_lg_u32 s7, 1
	v_lshl_add_u64 v[2:3], s[58:59], 0, v[130:131]
	s_cbranch_scc1 .LBB0_644
	s_barrier

.LBB0_657:
	s_mov_b32 s6, s101
	s_waitcnt vmcnt(0)
	s_waitcnt vmcnt(0)
	s_barrier
	s_and_saveexec_b64 s[8:9], s[80:81]
	s_cbranch_execz .LBB0_709
	v_readlane_b32 s98, v248, 1
	v_readlane_b32 s99, v248, 2
	v_mov_b32_e32 v0, 0x20ff0
	ds_read2_b32 v[2:3], v0 offset1:1
	v_mov_b32_e32 v1, 1
	v_mov_b32_e32 v4, s97
	v_lshlrev_b32_e32 v4, 8, v4
	s_add_u32 s98, s98, 0x1000
	s_addc_u32 s99, s99, 0
	s_nop 2
	global_atomic_add v5, v4, v1, s[98:99] offset:1024 sc0
	s_waitcnt vmcnt(0) lgkmcnt(0)
	v_mul_u32_u24_e32 v2, 5, v2
	v_mul_u32_u24_e32 v3, 5, v3
	v_add_u32_e32 v5, 1, v5
	v_cmp_ne_u32_e32 vcc, v5, v2
	v_mov_b32_e32 v6, 0x2400
	s_cbranch_vccnz .Lxb4_poll
	buffer_wbl2 sc1
	s_waitcnt vmcnt(0)
	global_atomic_add v6, v1, s[98:99]

.LBB0_733:
	s_waitcnt vmcnt(0)
	s_barrier
	s_and_saveexec_b64 s[0:1], s[80:81]
	s_cbranch_execz .LBB0_785
	v_readlane_b32 s98, v248, 1
	v_readlane_b32 s99, v248, 2
	v_mov_b32_e32 v0, 0x20ff0
	ds_read2_b32 v[2:3], v0 offset1:1
	v_mov_b32_e32 v1, 1
	v_mov_b32_e32 v4, s97
	v_lshlrev_b32_e32 v4, 8, v4
	s_add_u32 s98, s98, 0x1000
	s_addc_u32 s99, s99, 0
	s_nop 2
	global_atomic_add v5, v4, v1, s[98:99] offset:1024 sc0
	s_waitcnt vmcnt(0) lgkmcnt(0)
	v_mul_u32_u24_e32 v2, 6, v2
	v_mul_u32_u24_e32 v3, 6, v3
	v_add_u32_e32 v5, 1, v5
	v_cmp_ne_u32_e32 vcc, v5, v2
	v_mov_b32_e32 v6, 0x2400
	s_cbranch_vccnz .Lxb5_poll
	buffer_wbl2 sc1
	s_waitcnt vmcnt(0)
	global_atomic_add v6, v1, s[98:99]

.LBB0_1040:
	s_or_b64 exec, exec, s[24:25]
	s_waitcnt vmcnt(0)
	s_barrier
	s_and_saveexec_b64 s[0:1], s[80:81]
	s_cbranch_execz .LBB0_1092
	v_readlane_b32 s98, v248, 1
	v_readlane_b32 s99, v248, 2
	v_mov_b32_e32 v0, 0x20ff0
	ds_read2_b32 v[2:3], v0 offset1:1
	v_mov_b32_e32 v1, 1
	v_mov_b32_e32 v4, s97
	v_lshlrev_b32_e32 v4, 8, v4
	s_add_u32 s98, s98, 0x1000
	s_addc_u32 s99, s99, 0
	s_nop 2
	global_atomic_add v5, v4, v1, s[98:99] offset:1024 sc0
	s_waitcnt vmcnt(0) lgkmcnt(0)
	v_mul_u32_u24_e32 v2, 9, v2
	v_mul_u32_u24_e32 v3, 9, v3
	v_add_u32_e32 v5, 1, v5
	v_cmp_ne_u32_e32 vcc, v5, v2
	v_mov_b32_e32 v6, 0x2400
	s_cbranch_vccnz .Lxb8_poll
	buffer_wbl2 sc1
	s_waitcnt vmcnt(0)
	global_atomic_add v6, v1, s[98:99]

.LBB0_1108:
	s_waitcnt vmcnt(0)
	s_waitcnt vmcnt(0)
	s_barrier
	s_and_saveexec_b64 s[0:1], s[80:81]
	s_cbranch_execz .LBB0_1160
	v_readlane_b32 s98, v248, 1
	v_readlane_b32 s99, v248, 2
	v_mov_b32_e32 v0, 0x20ff0
	ds_read2_b32 v[2:3], v0 offset1:1
	v_mov_b32_e32 v1, 1
	v_mov_b32_e32 v4, s97
	v_lshlrev_b32_e32 v4, 8, v4
	s_add_u32 s98, s98, 0x1000
	s_addc_u32 s99, s99, 0
	s_nop 2
	global_atomic_add v5, v4, v1, s[98:99] offset:1024 sc0
	s_waitcnt vmcnt(0) lgkmcnt(0)
	v_mul_u32_u24_e32 v2, 10, v2
	v_mul_u32_u24_e32 v3, 10, v3
	v_add_u32_e32 v5, 1, v5
	v_cmp_ne_u32_e32 vcc, v5, v2
	v_mov_b32_e32 v6, 0x2400
	s_cbranch_vccnz .Lxb9_poll
	buffer_wbl2 sc1
	s_waitcnt vmcnt(0)
	global_atomic_add v6, v1, s[98:99]

.LBB0_1184:
	s_waitcnt vmcnt(0)
	s_barrier
	s_and_saveexec_b64 s[0:1], s[80:81]
	s_cbranch_execz .LBB0_1236
	v_readlane_b32 s98, v248, 1
	v_readlane_b32 s99, v248, 2
	v_mov_b32_e32 v0, 0x20ff0
	ds_read2_b32 v[2:3], v0 offset1:1
	v_mov_b32_e32 v1, 1
	v_mov_b32_e32 v4, s97
	v_lshlrev_b32_e32 v4, 8, v4
	s_add_u32 s98, s98, 0x1000
	s_addc_u32 s99, s99, 0
	s_nop 2
	global_atomic_add v5, v4, v1, s[98:99] offset:1024 sc0
	s_waitcnt vmcnt(0) lgkmcnt(0)
	v_mul_u32_u24_e32 v2, 11, v2
	v_mul_u32_u24_e32 v3, 11, v3
	v_add_u32_e32 v5, 1, v5
	v_cmp_ne_u32_e32 vcc, v5, v2
	v_mov_b32_e32 v6, 0x2400
	s_cbranch_vccnz .Lxb10_poll
	buffer_wbl2 sc1
	s_waitcnt vmcnt(0)
	global_atomic_add v6, v1, s[98:99]
